# MLA tile loop: next tile's LDS copy issued inside the second block's P*V MFMA chain instead of behind it (tile-end barrier no longer waits for the LDS writes)
# speedup vs baseline: 1.0058x; 1.0058x over previous
; #define LAS __attribute__((address_space(3)))
; template <int DQK, int DV, bool CAUSAL, int KT, bool PRIO>
; DI void attn_unit(const bf16_t* Qb, int qpitch, const bf16_t* Kb, int kpitch, const bf16_t* Vtb, int vpitch, bf16_t* Ob, int opitch, int q0, int nt, LAS unsigned char* lds, float kbound, const float* qgain, const int* qpos, float qscale) {
;     ...
;     auto lstore = [&](int buf) {
; #pragma unroll
;         for (int i = 0; i < NKR; ++i) { const int c = tid + i * 512; if (NKC % 512 == 0 || c < NKC) *(LAS u32x4*)(lds + buf * KBUF + (c / KCH) * KS + (c % KCH) * 16) = kreg[i]; }
; #pragma unroll
;         for (int i = 0; i < NVR; ++i) { const int c = tid + i * 512; LAS unsigned char* p = lds + VOFF + buf * VBUF + (c / VCH) * VS + (c % VCH) * 16;
;             *(LAS u32x2*)p = (u32x2){vreg[i].x, vreg[i].y}; *(LAS u32x2*)(p + 8) = (u32x2){vreg[i].z, vreg[i].w}; }
;     };
;     ...
;                     float ps = 0.f;
; #pragma unroll
;                     for (int i = 0; i < 16; ++i) { s0[i] = __builtin_amdgcn_exp2f(s0[i]); ps += s0[i]; asm volatile("" : "+v"(ps)); }
; #pragma unroll
;                     for (int i = 0; i < 16; ++i) { s1[i] = __builtin_amdgcn_exp2f(s1[i]); ps += s1[i]; asm volatile("" : "+v"(ps)); }
;                     lrun += ps;
;                     bf16x8 pf[4];
; #pragma unroll
;                     for (int sf = 0; sf < 2; ++sf) {
;                         u32x4 pw; pw.x = pk2(s0[8 * sf], s0[8 * sf + 1]); pw.y = pk2(s0[8 * sf + 2], s0[8 * sf + 3]); pw.z = pk2(s0[8 * sf + 4], s0[8 * sf + 5]); pw.w = pk2(s0[8 * sf + 6], s0[8 * sf + 7]); pf[sf] = __builtin_bit_cast(bf16x8, pw);
;                         u32x4 pv; pv.x = pk2(s1[8 * sf], s1[8 * sf + 1]); pv.y = pk2(s1[8 * sf + 2], s1[8 * sf + 3]); pv.z = pk2(s1[8 * sf + 4], s1[8 * sf + 5]); pv.w = pk2(s1[8 * sf + 6], s1[8 * sf + 7]); pf[2 + sf] = __builtin_bit_cast(bf16x8, pv);
;                     }
;                     __builtin_amdgcn_sched_barrier(0); __builtin_amdgcn_s_setprio(1); __builtin_amdgcn_sched_barrier(0);
; #pragma unroll
;                     for (int q4 = 0; q4 < 4; ++q4)
; #pragma unroll
;                         for (int d = 0; d < NDB; ++d) o[d] = MFMA32(vf[q4][d], pf[q4], o[d]);
;                     __builtin_amdgcn_sched_barrier(0); __builtin_amdgcn_s_setprio(0); __builtin_amdgcn_sched_barrier(0);
.LBB0_1514:
	s_nop 7
	v_exp_f32_e32 v14, v80
	v_exp_f32_e32 v15, v81
	v_exp_f32_e32 v80, v82
	v_exp_f32_e32 v81, v83
	v_add_f32_e32 v82, 0, v14
	v_exp_f32_e32 v83, v84
	v_add_f32_e32 v82, v15, v82
	v_exp_f32_e32 v84, v85
	v_add_f32_e32 v82, v80, v82
	v_exp_f32_e32 v85, v86
	v_add_f32_e32 v82, v81, v82
	v_exp_f32_e32 v86, v87
	v_add_f32_e32 v82, v83, v82
	v_exp_f32_e32 v87, v88
	v_add_f32_e32 v82, v84, v82
	v_exp_f32_e32 v88, v89
	v_add_f32_e32 v82, v85, v82
	v_exp_f32_e32 v89, v90
	v_add_f32_e32 v82, v86, v82
	v_exp_f32_e32 v90, v91
	v_add_f32_e32 v82, v87, v82
	v_exp_f32_e32 v91, v92
	v_add_f32_e32 v82, v88, v82
	v_exp_f32_e32 v92, v93
	v_add_f32_e32 v82, v89, v82
	v_exp_f32_e32 v93, v94
	v_add_f32_e32 v82, v90, v82
	v_exp_f32_e32 v94, v95
	v_add_f32_e32 v82, v91, v82
	v_exp_f32_e32 v95, v64
	v_add_f32_e32 v82, v92, v82
	v_exp_f32_e32 v194, v66
	v_add_f32_e32 v82, v93, v82
	v_exp_f32_e32 v195, v67
	v_add_f32_e32 v64, v94, v82
	v_exp_f32_e32 v82, v65
	v_exp_f32_e32 v197, v68
	v_add_f32_e32 v64, v95, v64
	v_exp_f32_e32 v198, v69
	v_add_f32_e32 v64, v82, v64
	v_exp_f32_e32 v199, v70
	v_add_f32_e32 v64, v194, v64
	v_exp_f32_e32 v71, v71
	v_add_f32_e32 v64, v195, v64
	v_exp_f32_e32 v200, v72
	v_add_f32_e32 v64, v197, v64
	v_exp_f32_e32 v201, v73
	v_add_f32_e32 v64, v198, v64
	v_exp_f32_e32 v202, v74
	v_add_f32_e32 v64, v199, v64
	v_exp_f32_e32 v203, v75
	v_add_f32_e32 v64, v71, v64
	v_exp_f32_e32 v204, v76
	v_add_f32_e32 v64, v200, v64
	v_exp_f32_e32 v205, v77
	v_add_f32_e32 v64, v201, v64
	v_exp_f32_e32 v206, v78
	v_add_f32_e32 v64, v202, v64
	v_exp_f32_e32 v79, v79
	v_add_f32_e32 v64, v203, v64
	v_cvt_pk_bf16_f32 v65, v80, v81
	v_add_f32_e32 v64, v204, v64
	v_cvt_pk_bf16_f32 v66, v83, v84
	v_add_f32_e32 v64, v205, v64
	v_cvt_pk_bf16_f32 v67, v85, v86
	v_add_f32_e32 v64, v206, v64
	v_cvt_pk_bf16_f32 v68, v95, v82
	v_add_f32_e32 v207, v79, v64
	v_cvt_pk_bf16_f32 v64, v14, v15
	v_cvt_pk_bf16_f32 v69, v194, v195
	v_cvt_pk_bf16_f32 v70, v197, v198
	v_cvt_pk_bf16_f32 v71, v199, v71
	v_cvt_pk_bf16_f32 v72, v87, v88
	v_cvt_pk_bf16_f32 v73, v89, v90
	v_cvt_pk_bf16_f32 v74, v91, v92
	v_cvt_pk_bf16_f32 v75, v93, v94
	v_cvt_pk_bf16_f32 v76, v200, v201
	v_cvt_pk_bf16_f32 v77, v202, v203
	v_cvt_pk_bf16_f32 v78, v204, v205
	v_cvt_pk_bf16_f32 v79, v206, v79
	s_setprio 1
	s_waitcnt lgkmcnt(0)
	s_waitcnt vmcnt(0)
	v_mfma_f32_32x32x16_bf16 v[32:47], v[156:159], v[64:67], v[32:47]
	v_add_f32_e32 v0, v0, v207
	s_xor_b32 s100, s75, 1
	s_mul_i32 s101, s100, 0x6800
	v_add3_u32 v250, s101, v178, v179
	v_mfma_f32_32x32x16_bf16 v[16:31], v[152:155], v[64:67], v[16:31]
	ds_write_b128 v250, v[96:99]
	v_add3_u32 v251, s101, v181, v182
	s_mulk_i32 s100, 0xdc00
	v_mfma_f32_32x32x16_bf16 v[32:47], v[140:143], v[72:75], v[32:47]
	ds_write_b128 v251, v[100:103]
	v_add3_u32 v250, s101, v183, v184
	s_add_i32 s101, s101, s100
	v_mfma_f32_32x32x16_bf16 v[16:31], v[148:151], v[72:75], v[16:31]
	ds_write_b128 v250, v[104:107]
	v_add_u32_e32 v251, s101, v185
	v_add3_u32 v251, v251, v186, s57
	v_mfma_f32_32x32x16_bf16 v[32:47], v[144:147], v[68:71], v[32:47]
	ds_write2_b64 v251, v[108:109], v[110:111] offset1:2
	v_add_u32_e32 v250, s101, v187
	v_add3_u32 v250, v250, v188, s57
	v_mfma_f32_32x32x16_bf16 v[16:31], v[10:13], v[68:71], v[16:31]
	ds_write2_b64 v250, v[112:113], v[114:115] offset1:2
	v_mfma_f32_32x32x16_bf16 v[32:47], v[6:9], v[76:79], v[32:47]
	v_mfma_f32_32x32x16_bf16 v[16:31], v[2:5], v[76:79], v[16:31]
	s_setprio 0
	s_branch .LBB0_1493
	s_nop 0
	s_nop 0
	s_nop 0
	s_nop 0
	s_nop 0
	s_nop 0
